# v39 + sample task: window-segment rows touched during the wave-0 top-k, branch-gate bg load issued with the G loads
# baseline (speedup 1.0000x reference)
; #define LAS __attribute__((address_space(3)))
; template <int NBL>
; __device__ __forceinline__ unsigned topk_select(const LAS float* sc  , int sub, int cur) {
;     unsigned v[NBL]; unsigned candm = 0u, forced = 0u;
; #pragma unroll
;     for (int e = 0; e < NBL; ++e) { const int j = sub * NBL + e; const bool cand = (j >= 1) && (j <= cur - 2);
;         v[e] = cand ? __float_as_uint(sc[j]) : 0u; if (cand) candm |= 1u << e;
;         if (j == 0 || j == cur || (j == cur - 1 && cur >= 1)) forced |= 1u << e; }
;     const int nf = cur == 0 ? 1 : (cur == 1 ? 2 : 3), kk = 16 - nf, ncand = cur - 2 > 0 ? cur - 2 : 0;
;     unsigned prefix = 0u;
;     {
;         unsigned ceil_ = 0xFFFFFFFFu; int taken = 0; bool done = ncand <= kk;
; __device__ __forceinline__ void sample_task_part2(const Prm& P, Ctx& C, int b, int kvh, int ts) {
;     ...
;     if (tid < 25) { const float* base;
;         if (tid < 16) { const int j = blist[tid]; base = j < 256 ? P.cache_s + ((size_t)P.page_table[b * NPAGES + (j >> 1)] * PAGE + (j & 1) * 64) * 256 : P.out + O_KSS + (size_t)(b * 4) * 256; }
;         else if (tid < 24) base = P.state_win + ((size_t)b * 512 + 64 * (tid - 16)) * 256;
.LBB0_1529:
	s_or_b64 exec, exec, s[0:1]
	v_readlane_b32 s2, v250, 20
	v_readlane_b32 s3, v250, 21
	v_readlane_b32 s4, v253, 28
	v_readlane_b32 s5, v253, 29
	s_add_u32 s2, s2, s4
	s_addc_u32 s3, s3, s5
	v_readlane_b32 s4, v251, 55
	s_lshl_b32 s4, s4, 10
	s_add_u32 s2, s2, s4
	s_addc_u32 s3, s3, 0
	s_lshl_b32 s4, s33, 2
	s_add_u32 s2, s2, s4
	s_addc_u32 s3, s3, 0
	v_mbcnt_lo_u32_b32 v234, -1, 0
	v_mbcnt_hi_u32_b32 v234, -1, v234
	v_lshlrev_b32_e32 v234, 10, v234
	global_load_dword v236, v234, s[2:3]
	global_load_dword v237, v234, s[2:3] offset:128
	global_load_dword v238, v234, s[2:3] offset:512
	global_load_dword v239, v234, s[2:3] offset:640
	v_mov_b32_e32 v32, 0x7ffffffe
	v_mov_b32_e32 v0, 0
	v_mov_b32_e32 v34, 0
	s_mov_b64 s[0:1], exec
	v_readlane_b32 s2, v253, 13
	v_readlane_b32 s3, v253, 14
	s_and_b64 s[2:3], s[0:1], s[2:3]
	s_mov_b64 exec, s[2:3]
	ds_read_b32 v34, v189
	v_bfrev_b32_e32 v32, -2
	s_or_b64 exec, exec, s[0:1]
	ds_read2_b32 v[30:31], v189 offset0:1 offset1:2
	ds_read2_b32 v[28:29], v189 offset0:3 offset1:4
	ds_read2_b32 v[26:27], v189 offset0:5 offset1:6
	ds_read2_b32 v[24:25], v189 offset0:7 offset1:8
	ds_read2_b32 v[22:23], v189 offset0:9 offset1:10
	ds_read2_b32 v[20:21], v189 offset0:11 offset1:12
	ds_read2_b32 v[18:19], v189 offset0:13 offset1:14
	ds_read2_b32 v[16:17], v189 offset0:15 offset1:16
	ds_read2_b32 v[14:15], v189 offset0:17 offset1:18
	ds_read2_b32 v[12:13], v189 offset0:19 offset1:20
	ds_read2_b32 v[10:11], v189 offset0:21 offset1:22
	ds_read2_b32 v[8:9], v189 offset0:23 offset1:24
	ds_read2_b32 v[6:7], v189 offset0:25 offset1:26
	ds_read2_b32 v[4:5], v189 offset0:27 offset1:28
	ds_read2_b32 v[2:3], v189 offset0:29 offset1:30
	s_mov_b64 s[0:1], exec
	v_readlane_b32 s2, v253, 21
	v_readlane_b32 s3, v253, 22
	s_and_b64 s[2:3], s[0:1], s[2:3]
	v_readlane_b32 s8, v251, 2
	s_mov_b64 exec, s[2:3]
	ds_read_b32 v0, v189 offset:124
	v_or_b32_e32 v32, 0x80000000, v32
	s_or_b64 exec, exec, s[0:1]
	s_mov_b64 s[2:3], 0
	v_mov_b32_e32 v35, -1
	v_mov_b32_e32 v33, 0
	v_mov_b32_e32 v36, 14
	v_mov_b32_e32 v37, 0
	s_branch .LBB0_1535

; __device__ __forceinline__ void sample_task_part2(const Prm& P, Ctx& C, int b, int kvh, int ts) {
;     ...
;     if (tid < 25) { const float* base;
;         if (tid < 16) { const int j = blist[tid]; base = j < 256 ? P.cache_s + ((size_t)P.page_table[b * NPAGES + (j >> 1)] * PAGE + (j & 1) * 64) * 256 : P.out + O_KSS + (size_t)(b * 4) * 256; }
;         else if (tid < 24) base = P.state_win + ((size_t)b * 512 + 64 * (tid - 16)) * 256;
;         else base = P.out + O_WINS + ((size_t)b * 512 + 508) * 256;
;         segb[tid] = (unsigned long long)(uintptr_t)base; }
;     __syncthreads();
.LBB0_1554:
	s_or_b64 exec, exec, s[0:1]
	s_branch .LBB0_1555
.Lpf_w:
	v_readlane_b32 s2, v250, 20
	v_readlane_b32 s3, v250, 21
	v_readlane_b32 s4, v253, 28
	v_readlane_b32 s5, v253, 29
	s_add_u32 s2, s2, s4
	s_addc_u32 s3, s3, s5
	v_readlane_b32 s4, v251, 55
	s_lshl_b32 s4, s4, 10
	s_add_u32 s2, s2, s4
	s_addc_u32 s3, s3, 0
	s_lshl_b32 s4, s33, 2
	s_add_u32 s2, s2, s4
	s_addc_u32 s3, s3, 0
	v_mbcnt_lo_u32_b32 v234, -1, 0
	v_mbcnt_hi_u32_b32 v234, -1, v234
	v_lshlrev_b32_e32 v234, 10, v234
	global_load_dword v236, v234, s[2:3]
	global_load_dword v237, v234, s[2:3] offset:128
	global_load_dword v238, v234, s[2:3] offset:512
	global_load_dword v239, v234, s[2:3] offset:640
.LBB0_1555:
	v_readlane_b32 s0, v251, 55
	s_waitcnt lgkmcnt(0)
	s_barrier
	s_waitcnt vmcnt(0)
	v_mbcnt_lo_u32_b32 v98, -1, 0
	v_mbcnt_hi_u32_b32 v98, -1, v98
	s_nop 0
	v_add_u32_e32 v117, s0, v98
	v_readlane_b32 s0, v250, 58
	v_readlane_b32 s1, v250, 59
	s_ashr_i32 s1, s0, 31
	v_writelane_b32 v250, s0, 58
	v_cmp_gt_i32_e32 vcc, 25, v117
	s_nop 0
	v_writelane_b32 v250, s1, 59
	s_and_saveexec_b64 s[0:1], vcc
	v_readlane_b32 s25, v251, 2
	s_cbranch_execz .LBB0_1569
	v_cmp_lt_i32_e32 vcc, 15, v117
	s_and_saveexec_b64 s[2:3], vcc
	s_xor_b64 s[2:3], exec, s[2:3]
	s_cbranch_execz .LBB0_1562
	v_cmp_ne_u32_e32 vcc, 24, v117
	s_and_saveexec_b64 s[4:5], vcc
	s_xor_b64 s[4:5], exec, s[4:5]
	s_cbranch_execz .LBB0_1559
	v_readlane_b32 s8, v250, 12
	v_readlane_b32 s12, v250, 16
	v_readlane_b32 s13, v250, 17
	v_readlane_b32 s16, v250, 20
	v_readlane_b32 s17, v250, 21
	v_mov_b32_e32 v0, 0xfffffc00
	s_mov_b64 s[12:13], s[16:17]
	v_readlane_b32 s6, v253, 28
	v_lshl_add_u32 v0, v117, 6, v0
	v_readlane_b32 s7, v253, 29
	s_add_u32 s6, s12, s6
	s_addc_u32 s7, s13, s7
	v_lshlrev_b64 v[2:3], 10, v[0:1]
	v_lshl_add_u64 v[2:3], s[6:7], 0, v[2:3]
	v_readlane_b32 s9, v250, 13
	v_readlane_b32 s10, v250, 14
	v_readlane_b32 s11, v250, 15
	v_readlane_b32 s14, v250, 18
	v_readlane_b32 s15, v250, 19
	v_readlane_b32 s18, v250, 22
	v_readlane_b32 s19, v250, 23
	v_readlane_b32 s20, v250, 24
	v_readlane_b32 s21, v250, 25
	v_readlane_b32 s22, v250, 26
	v_readlane_b32 s23, v250, 27

; #define LAS __attribute__((address_space(3)))
; __device__ __forceinline__ unsigned f2bf(float f) { unsigned u = __builtin_bit_cast(unsigned, f); return (u + 0x7fffu + ((u >> 16) & 1u)) >> 16; }
; __device__ __forceinline__ float ex2(float x) { return __builtin_amdgcn_exp2f(x); }
; __device__ __forceinline__ void sample_task_part2(const Prm& P, Ctx& C, int b, int kvh, int ts) {
;     ...
;     { const int br = tid >> 8, gq = (tid >> 6) & 3, d = tid & 63; float M = NEGB;
;         for (int w = 0; w < 8; ++w) M = fmaxf(M, part[((br * 8 + w) * 4 + gq) * 66]);
;         float L = 0.f, O = 0.f;
;         for (int w = 0; w < 8; ++w) { const LAS float* pp = part + ((br * 8 + w) * 4 + gq) * 66; const float f = ex2(pp[0] - M); L += pp[1] * f; O += pp[2 + d] * f; }
;         res[(br * 4 + gq) * 64 + d] = L > 0.f ? O / L : 0.f; }
;     __syncthreads();
;     if (tid < 256) { const int gq = tid >> 6, d = tid & 63, head = 4 * kvh + gq; const float* G = (const float*)(P.ws + WS_G) + row * 24 + head * 3;
;         float v = ocs[gq * 64 + d] + G[1] * res[gq * 64 + d] + G[2] * res[(4 + gq) * 64 + d];
;         v *= bf2f(((const bf16_t*)(P.ws + WS_BG))[row * 512 + head * 64 + d]);
;         ((bf16_t*)(P.ws + WS_H2))[row * 1024 + 512 + head * 64 + d] = (bf16_t)f2bf(v); }
.LBB0_1584:
	s_or_b64 exec, exec, s[0:1]
	v_readlane_b32 s0, v251, 30
	ds_write_b32 v0, v101 offset:57120
	v_ashrrev_i32_e32 v2, 6, v117
	v_lshl_add_u32 v0, v98, 2, s0
	ds_write_b32 v0, v113 offset:9248
	v_and_b32_e32 v22, 3, v2
	v_lshrrev_b32_e32 v0, 3, v117
	s_mov_b32 s0, 0x1fffffe0
	v_and_or_b32 v0, v0, s0, v22
	s_movk_i32 s0, 0x108
	v_mul_lo_u32 v0, v0, s0
	v_add_u32_e32 v20, 0, v0
	v_add_u32_e32 v0, 0xdc00, v20
	s_waitcnt lgkmcnt(0)
	s_barrier
	ds_read2_b64 v[4:7], v0 offset1:132
	v_add_u32_e32 v3, 0xe400, v20
	ds_read2_b64 v[8:11], v3 offset0:8 offset1:140
	v_add_u32_e32 v3, 0xec00, v20
	ds_read2_b64 v[12:15], v3 offset0:16 offset1:148
	v_add_u32_e32 v3, 0xf400, v20
	ds_read2_b64 v[16:19], v3 offset0:24 offset1:156
	s_mov_b32 s0, 0xf149f2ca
	s_waitcnt lgkmcnt(3)
	v_max3_f32 v0, v4, s0, v6
	s_waitcnt lgkmcnt(2)
	v_max3_f32 v0, v0, v8, v10
	s_waitcnt lgkmcnt(1)
	v_max3_f32 v0, v0, v12, v14
	s_waitcnt lgkmcnt(0)
	v_max3_f32 v23, v0, v16, v18
	v_and_b32_e32 v0, 63, v98
	v_sub_f32_e32 v3, v4, v23
	v_exp_f32_e32 v21, v3
	v_lshlrev_b32_e32 v3, 2, v0
	v_add_u32_e32 v24, v20, v3
	ds_read_b32 v4, v24 offset:56328
	s_waitcnt lgkmcnt(0)
	v_fma_f32 v25, v4, v21, 0
	v_sub_f32_e32 v4, v6, v23
	v_exp_f32_e32 v20, v4
	v_mov_b32_e32 v4, v7
	v_pk_mul_f32 v[4:5], v[4:5], v[20:21]
	s_nop 0
	v_add_f32_e32 v5, 0, v5
	v_add_f32_e32 v21, v4, v5
	ds_read_b32 v4, v24 offset:57384
	ds_read_b32 v5, v24 offset:58440
	s_waitcnt lgkmcnt(1)
	v_fmac_f32_e32 v25, v20, v4
	v_sub_f32_e32 v4, v8, v23
	v_exp_f32_e32 v4, v4
	s_waitcnt lgkmcnt(0)
	v_fmac_f32_e32 v25, v4, v5
	v_sub_f32_e32 v5, v10, v23
	v_exp_f32_e32 v5, v5
	v_mov_b32_e32 v10, v9
	v_pk_mul_f32 v[6:7], v[4:5], v[10:11]
	s_nop 0
	v_add_f32_e32 v4, v21, v6
	v_add_f32_e32 v8, v4, v7
	ds_read_b32 v4, v24 offset:59496
	s_waitcnt lgkmcnt(0)
	v_fmac_f32_e32 v25, v5, v4
	v_sub_f32_e32 v4, v12, v23
	ds_read_b32 v5, v24 offset:60552
	v_exp_f32_e32 v4, v4
	s_waitcnt lgkmcnt(0)
	v_fmac_f32_e32 v25, v4, v5
	v_sub_f32_e32 v5, v14, v23
	v_exp_f32_e32 v5, v5
	v_mov_b32_e32 v14, v13
	v_pk_mul_f32 v[6:7], v[4:5], v[14:15]
	s_nop 0
	v_add_f32_e32 v4, v8, v6
	v_add_f32_e32 v8, v4, v7
	ds_read_b32 v4, v24 offset:61608
	s_waitcnt lgkmcnt(0)
	v_fmac_f32_e32 v25, v5, v4
	v_sub_f32_e32 v4, v16, v23
	ds_read_b32 v5, v24 offset:62664
	v_exp_f32_e32 v4, v4
	s_waitcnt lgkmcnt(0)
	v_fmac_f32_e32 v25, v4, v5
	v_sub_f32_e32 v5, v18, v23
	v_exp_f32_e32 v5, v5
	v_mov_b32_e32 v18, v17
	v_pk_mul_f32 v[6:7], v[4:5], v[18:19]
	s_nop 0
	v_add_f32_e32 v4, v8, v6
	ds_read_b32 v6, v24 offset:63720
	v_add_f32_e32 v4, v4, v7
	v_cmp_lt_f32_e64 s[0:1], 0, v4
	s_waitcnt lgkmcnt(0)
	v_fmac_f32_e32 v25, v5, v6
	v_div_scale_f32 v5, s[2:3], v4, v4, v25
	v_rcp_f32_e32 v6, v5
	s_nop 0
	v_fma_f32 v7, -v5, v6, 1.0
	v_fmac_f32_e32 v6, v7, v6
	v_div_scale_f32 v7, vcc, v25, v4, v25
	v_mul_f32_e32 v8, v7, v6
	v_fma_f32 v9, -v5, v8, v7
	v_fmac_f32_e32 v8, v9, v6
	v_fma_f32 v5, -v5, v8, v7
	v_div_fmas_f32 v5, v5, v6, v8
	v_div_fixup_f32 v4, v5, v4, v25
	v_cndmask_b32_e64 v4, 0, v4, s[0:1]
	v_and_b32_e32 v5, 0x3fffff00, v117
	v_readlane_b32 s0, v251, 62
	v_lshlrev_b32_e32 v6, 8, v22
	s_nop 0
	v_lshl_add_u32 v5, v5, 2, s0
	s_movk_i32 s0, 0x100
	v_add3_u32 v5, v5, v6, v3
	v_cmp_gt_i32_e32 vcc, s0, v117
	ds_write_b32 v5, v4
	s_waitcnt lgkmcnt(0)
	s_barrier
	s_and_saveexec_b64 s[0:1], vcc
	s_cbranch_execz .LBB0_1486
	v_readlane_b32 s2, v250, 58
	v_readlane_b32 s3, v250, 59
	s_add_u32 s2, s2, s25
	s_addc_u32 s3, s3, 0
	s_add_u32 s2, s2, 0x8000
	s_addc_u32 s3, s3, 0
	v_readlane_b32 s4, v253, 25
	s_mul_hi_u32 s5, s2, 0x60
	v_readlane_b32 s6, v251, 21
	v_add_u32_e32 v6, s4, v2
	s_mul_i32 s4, s3, 0x60
	s_add_i32 s5, s5, s4
	s_mul_i32 s4, s2, 0x60
	s_add_u32 s4, s6, s4
	v_readlane_b32 s6, v251, 22
	v_lshl_add_u32 v4, v6, 1, v6
	s_addc_u32 s5, s6, s5
	v_ashrrev_i32_e32 v5, 31, v4
	v_lshl_add_u64 v[4:5], v[4:5], 2, s[4:5]
	global_load_dwordx2 v[4:5], v[4:5], off offset:4
	v_lshlrev_b32_e32 v2, 2, v117
	v_and_b32_e32 v8, 0x3fffffc0, v117
	v_add_u32_e32 v7, 0, v2
	v_readlane_b32 s4, v251, 62
	v_lshlrev_b32_e32 v8, 2, v8
	v_add_u32_e32 v7, 0x12600, v7
	v_add_u32_e32 v2, s4, v2
	v_add3_u32 v3, s4, v8, v3
	ds_read_b32 v7, v7
	ds_read_b32 v2, v2
	ds_read_b32 v3, v3 offset:1024
	s_lshl_b64 s[4:5], s[2:3], 10
	v_readlane_b32 s6, v251, 31
	s_add_u32 s4, s6, s4
	v_readlane_b32 s6, v251, 32
	s_addc_u32 s5, s6, s5
	v_lshlrev_b32_e32 v0, 1, v0
	s_lshl_b64 s[2:3], s[2:3], 11
	v_lshlrev_b32_e32 v10, 6, v6
	v_ashrrev_i32_e32 v11, 31, v10
	v_lshlrev_b64 v[10:11], 1, v[10:11]
	v_lshl_add_u64 v[12:13], s[4:5], 0, v[10:11]
	v_lshl_add_u64 v[12:13], v[12:13], 0, v[0:1]
	global_load_ushort v14, v[12:13], off
	s_waitcnt vmcnt(1) lgkmcnt(0)
	v_pk_mul_f32 v[2:3], v[4:5], v[2:3]
	s_nop 0
	v_add_f32_e32 v2, v7, v2
	v_add_f32_e32 v7, v2, v3
	v_readlane_b32 s4, v251, 33
	s_add_u32 s2, s4, s2
	v_readlane_b32 s4, v251, 34
	s_addc_u32 s3, s4, s3
	v_lshl_add_u64 v[2:3], s[2:3], 0, v[10:11]
	v_lshl_add_u64 v[2:3], v[2:3], 0, v[0:1]
	s_waitcnt vmcnt(0)
	v_lshlrev_b32_e32 v4, 16, v14
	v_mul_f32_e32 v4, v7, v4
	v_cvt_pk_bf16_f32 v4, v4, v4
	global_store_short_d16_hi v[2:3], v4, off
	s_branch .LBB0_1486
